# pvprio + attention peephole: 5 row-sum add-zero inits folded, 2 alpha register copies replaced by op_sel high-half broadcast
# speedup vs baseline: 1.0036x; 1.0036x over previous
; #define GAS __attribute__((address_space(1)))
; #define DMA_TILE(t) do { const unsigned sl_ = (unsigned)__builtin_amdgcn_readfirstlane(ring0 + (unsigned)(((t) + base) % 3) * SLOT); \
;         glds16kv(loffk, loffv, kg + (size_t)(t) * 64 * PITCH, vg + (size_t)(t) * 64 * PITCH, sl_); } while (0)
; #define DMA_NEXT(i) do { const unsigned sl_ = (unsigned)__builtin_amdgcn_readfirstlane(ring0 + (unsigned)((nT + (i) + base) % 3) * SLOT); \
;         glds16kv(loffk, loffv, nK + (size_t)(i) * 64 * PITCH, nV + (size_t)(i) * 64 * PITCH, sl_); } while (0)
; template <int MODE> ...
;     ...
;     auto head = [&](const int t) __attribute__((always_inline)) {
;         if (t >= 2) { if (t + 1 < nT || nK) asm volatile("s_waitcnt vmcnt(2)" ::: "memory"); else asm volatile("s_waitcnt vmcnt(0)" ::: "memory"); }
;         __builtin_amdgcn_s_barrier();
;         if (t + 2 < nT) DMA_TILE(t + 2); else if (nK) DMA_NEXT(t + 2 - nT);
;     };
;     auto body = [&](const int t) __attribute__((always_inline)) {
;         if (t >= act0 && t < act0 + actn) {
;     ...
;     { const GAS bf16_t* qs = nQ ? (const GAS bf16_t*)nQ : (const GAS bf16_t*)proj + (size_t)qtok0 * NIN + qcol;
; #pragma unroll
;       for (int jj = 0; jj < 2; ++jj)
; #pragma unroll
;           for (int ks = 0; ks < 2; ++ks) qn[jj][ks] = *(const GAS bf16x8*)(qs + (size_t)(16 * jj) * NIN + 32 * ks + qoff); }
.LBB0_283:
	s_add_i32 s42, s86, s26
	s_add_i32 s0, s42, 1
	s_mul_hi_i32 s14, s0, 0x55555556
	s_lshr_b32 s15, s14, 31
	s_add_i32 s14, s14, s15
	s_mul_i32 s14, s14, 3
	s_sub_i32 s0, s0, s14
	s_lshl_b32 s0, s0, 14
	s_add_i32 s0, s0, s94
	s_add_u32 s34, s34, 0x48000
	s_addc_u32 s35, s35, 0
	s_add_u32 s30, s30, 0x48000
	s_barrier
	s_addc_u32 s31, s31, 0
	s_mov_b32 m0, s0
	s_nop 0
	global_load_lds_dwordx4 v84, s[34:35]
	s_add_u32 m0, m0, 0x2000
	s_nop 0
	global_load_lds_dwordx4 v85, s[30:31]
	v_lshl_add_u64 v[6:7], v[82:83], 1, s[38:39]
	global_load_dwordx4 v[2:5], v[6:7], off
	global_load_dwordx4 v[10:13], v[6:7], off offset:64
	v_add_co_u32_e32 v6, vcc, 0x12000, v6
	s_cmp_gt_u32 s40, s27
	s_nop 0
	v_addc_co_u32_e32 v7, vcc, 0, v7, vcc
	global_load_dwordx4 v[14:17], v[6:7], off
	s_nop 0
	global_load_dwordx4 v[6:9], v[6:7], off offset:64
	s_cselect_b64 s[30:31], -1, 0
	s_add_i32 s0, s23, 8
	s_cmp_le_i32 s26, s0
	s_cselect_b64 s[26:27], -1, 0
	s_and_b64 s[26:27], s[30:31], s[26:27]
	s_and_b64 vcc, exec, s[26:27]
	s_cbranch_vccz .LBB0_285
; #define LAS __attribute__((address_space(3)))
; template <int MODE> ...
;     ...
;             if (MODE == 1) { const int ks = ktok0 + 64 * t + 32 * hf;
;                 if (ks + 31 < qtok0 - 128 || ks > qtok0 + 31 + 128) continue; }
;             bf16x8 kf[2][2][2];
; #pragma unroll
;             for (int jj = 0; jj < 2; ++jj)
; #pragma unroll
;                 for (int kt = 0; kt < 2; ++kt)
; #pragma unroll
;                     for (int ks = 0; ks < 2; ++ks) kf[jj][kt][ks] = *(const LAS bf16x8*)(Sl + kad[jj][ks] + (32 * hf + 16 * kt) * 128);
;             f32x4 bb[2][2];
; #pragma unroll
;             for (int jj = 0; jj < 2; ++jj) { const LAS f32x4* bl = bcp + ((MODE == 0) ? (dr0 + t - act0) * 8 : 16 * t + 8 * hf) + bofs[jj];
; #pragma unroll
;                 for (int kt = 0; kt < 2; ++kt) bb[jj][kt] = bl[4 * kt]; }
;             s16x4 vlo[2][4], vhi[2][4];
; #pragma unroll
;             for (int jj = 0; jj < 2; ++jj)
; #pragma unroll
;                 for (int dt = 0; dt < 4; ++dt) { const LAS unsigned char* vp = Sl + vad[jj] + (32 * hf) * 128 + ((dt ^ sv) << 5);
;                     vlo[jj][dt] = __builtin_bit_cast(s16x4, __builtin_amdgcn_ds_read_tr16_b64_v4i16((LAS s16x4*)(vp)));
;                     vhi[jj][dt] = __builtin_bit_cast(s16x4, __builtin_amdgcn_ds_read_tr16_b64_v4i16((LAS s16x4*)(vp + 2048))); }
;             __builtin_amdgcn_sched_barrier(0);
;             f32x4 s[2][2];
; #pragma unroll
;             for (int jj = 0; jj < 2; ++jj)
; #pragma unroll
;                 for (int kt = 0; kt < 2; ++kt) { f32x4 a = (MODE == 0) ? bb[jj][kt] + mneg[jj][kt] : bb[jj][kt];
;                     a = __builtin_amdgcn_mfma_f32_16x16x32_bf16(kf[jj][kt][0], qf[jj][0], a, 0, 0, 0);
;                     s[jj][kt] = __builtin_amdgcn_mfma_f32_16x16x32_bf16(kf[jj][kt][1], qf[jj][1], a, 0, 0, 0); }
;             u32x4 pw[2];
; #pragma unroll
;             for (int jj = 0; jj < 2; ++jj) {
;                 const float tm = vmax3(vmax3(s[jj][0][0], s[jj][0][1], s[jj][0][2]), vmax3(s[jj][0][3], s[jj][1][0], s[jj][1][1]), vmax3(s[jj][1][2], s[jj][1][3], s[jj][1][3]));
;                 const float mn = quad_max3(mrun[jj], tm);
;                 const float alpha = __builtin_amdgcn_exp2f(mrun[jj] - mn);
;                 mrun[jj] = mn;
;                 float rsum = 0.f;
; #pragma unroll
;                 for (int kt = 0; kt < 2; ++kt)
; #pragma unroll
	s_add_i32 s0, s41, s86
	s_mul_hi_i32 s14, s0, 0x55555556
	s_lshr_b32 s15, s14, 31
	s_add_i32 s14, s14, s15
	s_mul_i32 s14, s14, 3
	s_sub_i32 s0, s0, s14
	s_lshl_b32 s0, s0, 14
	s_sub_i32 s14, s41, s23
	s_add_i32 s0, s0, 0
	s_add_i32 s14, s14, s25
	v_add_u32_e32 v0, s0, v89
	s_lshl_b32 s14, s14, 7
	v_add_u32_e32 v66, s0, v88
	ds_read_b128 v[126:129], v0
	ds_read_b128 v[130:133], v0 offset:2048
	ds_read_b128 v[134:137], v66
	ds_read_b128 v[138:141], v66 offset:2048
	v_add_u32_e32 v0, s0, v92
	s_add_i32 s24, s24, s14
	v_add_u32_e32 v66, s0, v91
	ds_read_b128 v[142:145], v0
	ds_read_b128 v[146:149], v0 offset:2048
	ds_read_b128 v[150:153], v66
	ds_read_b128 v[154:157], v66 offset:2048
	v_lshl_add_u32 v0, v87, 4, s24
	ds_read_b128 v[158:161], v0
	ds_read_b128 v[162:165], v0 offset:64
	v_lshl_add_u32 v0, v90, 4, s24
	ds_read_b128 v[166:169], v0
	ds_read_b128 v[170:173], v0 offset:64
	v_lshlrev_b32_e32 v0, 5, v93
	v_add3_u32 v66, v86, v122, s0
	v_add_u32_e32 v67, v66, v0
	v_xor_b32_e32 v68, 32, v0
	v_add_u32_e32 v69, v66, v68
	ds_read_b64_tr_b16 v[94:95], v67 offset:8192
	ds_read_b64_tr_b16 v[96:97], v67 offset:10240
	ds_read_b64_tr_b16 v[90:91], v69 offset:8192
	ds_read_b64_tr_b16 v[92:93], v69 offset:10240
	v_xor_b32_e32 v67, 64, v0
	v_xor_b32_e32 v70, 0x60, v0
	v_add_u32_e32 v69, v66, v67
	v_add_u32_e32 v66, v66, v70
	ds_read_b64_tr_b16 v[86:87], v69 offset:8192
	ds_read_b64_tr_b16 v[88:89], v69 offset:10240
	ds_read_b64_tr_b16 v[82:83], v66 offset:8192
	ds_read_b64_tr_b16 v[84:85], v66 offset:10240
	v_add3_u32 v66, v123, v122, s0
	v_add_u32_e32 v0, v66, v0
	v_add_u32_e32 v68, v66, v68
	ds_read_b64_tr_b16 v[78:79], v0 offset:8192
	ds_read_b64_tr_b16 v[80:81], v0 offset:10240
	ds_read_b64_tr_b16 v[74:75], v68 offset:8192
	ds_read_b64_tr_b16 v[76:77], v68 offset:10240
	v_add_u32_e32 v0, v66, v67
	v_add_u32_e32 v68, v66, v70
	ds_read_b64_tr_b16 v[70:71], v0 offset:8192
	ds_read_b64_tr_b16 v[72:73], v0 offset:10240
	ds_read_b64_tr_b16 v[66:67], v68 offset:8192
	ds_read_b64_tr_b16 v[68:69], v68 offset:10240
	s_waitcnt lgkmcnt(14)
	v_pk_add_f32 v[112:113], v[112:113], v[160:161]
	v_pk_add_f32 v[110:111], v[110:111], v[158:159]
	v_pk_add_f32 v[114:115], v[114:115], v[164:165]
	v_pk_add_f32 v[100:101], v[100:101], v[170:171]
	v_mfma_f32_16x16x32_bf16 v[110:113], v[126:129], v[30:33], v[110:113]
	v_mfma_f32_16x16x32_bf16 v[126:129], v[134:137], v[26:29], v[110:113]
	s_nop 6
	v_pk_add_f32 v[112:113], v[108:109], v[162:163]
	v_maximum3_f32 v0, v126, v127, v128
	v_pk_add_f32 v[108:109], v[106:107], v[168:169]
	v_mfma_f32_16x16x32_bf16 v[30:33], v[130:133], v[30:33], v[112:115]
	v_pk_add_f32 v[106:107], v[102:103], v[166:167]
	v_pk_add_f32 v[102:103], v[104:105], v[172:173]
	v_mfma_f32_16x16x32_bf16 v[26:29], v[138:141], v[26:29], v[30:33]
	s_nop 7
	v_maximum3_f32 v30, v129, v26, v27
	v_maximum3_f32 v31, v28, v29, v29
	v_maximum3_f32 v0, v0, v30, v31
	v_mov_b32_e32 v104, v0
	s_nop 1
	v_permlane16_swap_b32_e32 v0, v104
	v_mfma_f32_16x16x32_bf16 v[30:33], v[142:145], v[22:25], v[106:109]
	v_maximum3_f32 v0, v0, v104, v104
	v_mov_b32_e32 v104, v0
	s_nop 1
	v_permlane32_swap_b32_e32 v0, v104
	v_mfma_f32_16x16x32_bf16 v[22:25], v[146:149], v[22:25], v[100:103]
	v_maximum3_f32 v0, v125, v0, v104
	v_mfma_f32_16x16x32_bf16 v[30:33], v[150:153], v[18:21], v[30:33]
	s_nop 0
	v_sub_f32_e32 v100, v125, v0
	v_exp_f32_e32 v122, v100
	v_sub_f32_e32 v101, v126, v0
	v_mfma_f32_16x16x32_bf16 v[18:21], v[154:157], v[18:21], v[22:25]
	v_exp_f32_e32 v104, v101
	v_pk_mul_f32 v[60:61], v[60:61], v[122:123] op_sel_hi:[1,0]
	v_pk_mul_f32 v[58:59], v[58:59], v[122:123] op_sel_hi:[1,0]
	v_sub_f32_e32 v22, v127, v0
	v_exp_f32_e32 v106, v22
	v_sub_f32_e32 v22, v128, v0
	v_exp_f32_e32 v108, v22
	v_sub_f32_e32 v22, v129, v0
	v_exp_f32_e32 v110, v22
	v_sub_f32_e32 v22, v26, v0
	v_exp_f32_e32 v112, v22
	v_sub_f32_e32 v22, v27, v0
	v_exp_f32_e32 v114, v22
	v_sub_f32_e32 v22, v28, v0
	v_sub_f32_e32 v0, v29, v0
	v_exp_f32_e32 v126, v22
	v_exp_f32_e32 v128, v0
	v_pk_mul_f32 v[22:23], v[54:55], v[122:123] op_sel_hi:[1,0]
	v_maximum3_f32 v0, v30, v31, v32
	v_maximum3_f32 v54, v33, v18, v19
	v_maximum3_f32 v55, v20, v21, v21
	v_maximum3_f32 v0, v0, v54, v55
	v_mov_b32_e32 v54, v0
	s_nop 1
	v_permlane16_swap_b32_e32 v0, v54
	v_maximum3_f32 v0, v0, v54, v54
	v_mov_b32_e32 v54, v0
	s_nop 1
	v_permlane32_swap_b32_e32 v0, v54
	v_maximum3_f32 v0, v124, v0, v54
	v_sub_f32_e32 v30, v30, v0
	v_exp_f32_e32 v105, v30
	v_sub_f32_e32 v30, v31, v0
	v_exp_f32_e32 v107, v30
	v_sub_f32_e32 v30, v32, v0
	v_sub_f32_e32 v18, v18, v0
	v_exp_f32_e32 v109, v30
	v_sub_f32_e32 v30, v33, v0
	v_exp_f32_e32 v113, v18
	v_sub_f32_e32 v18, v19, v0
	v_sub_f32_e32 v54, v124, v0
	v_exp_f32_e32 v111, v30
	v_exp_f32_e32 v115, v18
	v_sub_f32_e32 v18, v20, v0
	v_pk_mul_f32 v[24:25], v[56:57], v[122:123] op_sel_hi:[1,0]
	v_pk_mul_f32 v[28:29], v[64:65], v[122:123] op_sel_hi:[1,0]
	v_pk_mul_f32 v[26:27], v[62:63], v[122:123] op_sel_hi:[1,0]
	v_pk_mul_f32 v[52:53], v[52:53], v[122:123] op_sel_hi:[1,0]
	v_pk_mul_f32 v[50:51], v[50:51], v[122:123] op_sel_hi:[1,0]
	v_exp_f32_e32 v127, v18
	v_sub_f32_e32 v0, v21, v0
	v_exp_f32_e32 v123, v54
	v_exp_f32_e32 v129, v0
	v_pk_add_f32 v[18:19], v[104:105], v[106:107]
	v_cvt_pk_bf16_f32 v100, v104, v106
	v_pk_add_f32 v[18:19], v[108:109], v[18:19]
	v_cvt_pk_bf16_f32 v101, v108, v110
	v_pk_add_f32 v[18:19], v[110:111], v[18:19]
	v_cvt_pk_bf16_f32 v102, v112, v114
	v_cvt_pk_bf16_f32 v103, v126, v128
	v_pk_add_f32 v[18:19], v[112:113], v[18:19]
	v_mov_b32_e32 v0, v123
	v_mfma_f32_16x16x32_bf16 v[54:57], v[94:97], v[100:103], v[22:25]
	v_pk_mul_f32 v[20:21], v[48:49], v[0:1] op_sel_hi:[1,0]
	s_setprio 1
	s_waitcnt lgkmcnt(12)
	v_mfma_f32_16x16x32_bf16 v[62:65], v[90:93], v[100:103], v[26:29]
	v_cvt_pk_bf16_f32 v22, v105, v107
	v_cvt_pk_bf16_f32 v23, v109, v111
	v_cvt_pk_bf16_f32 v24, v113, v115
	v_pk_add_f32 v[26:27], v[114:115], v[18:19]
	v_pk_mul_f32 v[18:19], v[46:47], v[0:1] op_sel_hi:[1,0]
	v_cvt_pk_bf16_f32 v25, v127, v129
	s_waitcnt lgkmcnt(10)
	v_mfma_f32_16x16x32_bf16 v[58:61], v[86:89], v[100:103], v[58:61]
	v_pk_add_f32 v[26:27], v[126:127], v[26:27]
	v_pk_add_f32 v[26:27], v[128:129], v[26:27]
	s_waitcnt lgkmcnt(6)
	v_mfma_f32_16x16x32_bf16 v[46:49], v[78:81], v[22:25], v[18:21]
	v_fma_f32 v98, v98, v122, v26
	v_fma_f32 v99, v99, v123, v27
	s_nop 0
	v_pk_mul_f32 v[20:21], v[44:45], v[0:1] op_sel_hi:[1,0]
	v_pk_mul_f32 v[18:19], v[42:43], v[0:1] op_sel_hi:[1,0]
	v_mfma_f32_16x16x32_bf16 v[50:53], v[82:85], v[100:103], v[50:53]
	s_waitcnt lgkmcnt(4)
	v_mfma_f32_16x16x32_bf16 v[42:45], v[74:77], v[22:25], v[18:21]
	s_nop 2
	v_pk_mul_f32 v[20:21], v[40:41], v[0:1] op_sel_hi:[1,0]
	v_pk_mul_f32 v[18:19], v[38:39], v[0:1] op_sel_hi:[1,0]
	s_waitcnt lgkmcnt(2)
	s_nop 0
	v_mfma_f32_16x16x32_bf16 v[38:41], v[70:73], v[22:25], v[18:21]
	s_nop 2
	v_pk_mul_f32 v[20:21], v[36:37], v[0:1] op_sel_hi:[1,0]
	v_pk_mul_f32 v[18:19], v[34:35], v[0:1] op_sel_hi:[1,0]
	s_waitcnt lgkmcnt(0)
	s_setprio 0
	s_nop 0
	v_mfma_f32_16x16x32_bf16 v[34:37], v[66:69], v[22:25], v[18:21]

; #define LAS __attribute__((address_space(3)))
; template <int MODE> ...
;     ...
;             if (MODE == 1) { const int ks = ktok0 + 64 * t + 32 * hf;
;                 if (ks + 31 < qtok0 - 128 || ks > qtok0 + 31 + 128) continue; }
;             bf16x8 kf[2][2][2];
; #pragma unroll
;             for (int jj = 0; jj < 2; ++jj)
; #pragma unroll
;                 for (int kt = 0; kt < 2; ++kt)
; #pragma unroll
;                     for (int ks = 0; ks < 2; ++ks) kf[jj][kt][ks] = *(const LAS bf16x8*)(Sl + kad[jj][ks] + (32 * hf + 16 * kt) * 128);
;             f32x4 bb[2][2];
; #pragma unroll
;             for (int jj = 0; jj < 2; ++jj) { const LAS f32x4* bl = bcp + ((MODE == 0) ? (dr0 + t - act0) * 8 : 16 * t + 8 * hf) + bofs[jj];
; #pragma unroll
;                 for (int kt = 0; kt < 2; ++kt) bb[jj][kt] = bl[4 * kt]; }
;             s16x4 vlo[2][4], vhi[2][4];
; #pragma unroll
;             for (int jj = 0; jj < 2; ++jj)
; #pragma unroll
;                 for (int dt = 0; dt < 4; ++dt) { const LAS unsigned char* vp = Sl + vad[jj] + (32 * hf) * 128 + ((dt ^ sv) << 5);
;                     vlo[jj][dt] = __builtin_bit_cast(s16x4, __builtin_amdgcn_ds_read_tr16_b64_v4i16((LAS s16x4*)(vp)));
;                     vhi[jj][dt] = __builtin_bit_cast(s16x4, __builtin_amdgcn_ds_read_tr16_b64_v4i16((LAS s16x4*)(vp + 2048))); }
;             __builtin_amdgcn_sched_barrier(0);
;             f32x4 s[2][2];
; #pragma unroll
;             for (int jj = 0; jj < 2; ++jj)
; #pragma unroll
;                 for (int kt = 0; kt < 2; ++kt) { f32x4 a = (MODE == 0) ? bb[jj][kt] + mneg[jj][kt] : bb[jj][kt];
;                     a = __builtin_amdgcn_mfma_f32_16x16x32_bf16(kf[jj][kt][0], qf[jj][0], a, 0, 0, 0);
;                     s[jj][kt] = __builtin_amdgcn_mfma_f32_16x16x32_bf16(kf[jj][kt][1], qf[jj][1], a, 0, 0, 0); }
;             u32x4 pw[2];
; #pragma unroll
;             for (int jj = 0; jj < 2; ++jj) {
;                 const float tm = vmax3(vmax3(s[jj][0][0], s[jj][0][1], s[jj][0][2]), vmax3(s[jj][0][3], s[jj][1][0], s[jj][1][1]), vmax3(s[jj][1][2], s[jj][1][3], s[jj][1][3]));
;                 const float mn = quad_max3(mrun[jj], tm);
;                 const float alpha = __builtin_amdgcn_exp2f(mrun[jj] - mn);
;                 mrun[jj] = mn;
;                 float rsum = 0.f;
; #pragma unroll
;                 for (int kt = 0; kt < 2; ++kt)
; #pragma unroll
.LBB0_298:
	s_add_i32 s0, s86, 1
	s_mul_hi_i32 s14, s0, 0x55555556
	s_lshr_b32 s15, s14, 31
	s_add_i32 s14, s14, s15
	s_mul_i32 s14, s14, 3
	s_sub_i32 s0, s0, s14
	s_lshl_b32 s0, s0, 14
	s_add_i32 s0, s0, 0
	v_add_u32_e32 v0, s0, v89
	s_lshl_b32 s14, s52, 7
	v_add_u32_e32 v2, s0, v88
	ds_read_b128 v[126:129], v0
	ds_read_b128 v[130:133], v0 offset:2048
	ds_read_b128 v[134:137], v2
	ds_read_b128 v[138:141], v2 offset:2048
	v_add_u32_e32 v0, s0, v92
	s_add_i32 s14, s24, s14
	v_add_u32_e32 v2, s0, v91
	ds_read_b128 v[142:145], v0
	ds_read_b128 v[146:149], v0 offset:2048
	ds_read_b128 v[150:153], v2
	ds_read_b128 v[154:157], v2 offset:2048
	v_lshl_add_u32 v0, v87, 4, s14
	ds_read_b128 v[158:161], v0 offset:128
	ds_read_b128 v[162:165], v0 offset:192
	v_lshl_add_u32 v0, v90, 4, s14
	ds_read_b128 v[166:169], v0 offset:128
	ds_read_b128 v[170:173], v0 offset:192
	v_add3_u32 v0, v86, v122, s0
	v_add_u32_e32 v2, v0, v94
	v_add_u32_e32 v3, v0, v95
	ds_read_b64_tr_b16 v[78:79], v2 offset:8192
	ds_read_b64_tr_b16 v[80:81], v2 offset:10240
	ds_read_b64_tr_b16 v[74:75], v3 offset:8192
	ds_read_b64_tr_b16 v[76:77], v3 offset:10240
	v_add_u32_e32 v2, v0, v96
	v_add_u32_e32 v0, v0, v97
	ds_read_b64_tr_b16 v[70:71], v2 offset:8192
	ds_read_b64_tr_b16 v[72:73], v2 offset:10240
	ds_read_b64_tr_b16 v[66:67], v0 offset:8192
	ds_read_b64_tr_b16 v[68:69], v0 offset:10240
	v_add3_u32 v0, v123, v122, s0
	v_add_u32_e32 v2, v0, v94
	v_add_u32_e32 v3, v0, v95
	ds_read_b64_tr_b16 v[14:15], v2 offset:8192
	ds_read_b64_tr_b16 v[16:17], v2 offset:10240
	ds_read_b64_tr_b16 v[10:11], v3 offset:8192
	ds_read_b64_tr_b16 v[12:13], v3 offset:10240
	v_add_u32_e32 v2, v0, v96
	v_add_u32_e32 v0, v0, v97
	ds_read_b64_tr_b16 v[6:7], v2 offset:8192
	ds_read_b64_tr_b16 v[8:9], v2 offset:10240
	ds_read_b64_tr_b16 v[2:3], v0 offset:8192
	ds_read_b64_tr_b16 v[4:5], v0 offset:10240
	s_waitcnt lgkmcnt(14)
	v_pk_add_f32 v[160:161], v[112:113], v[160:161]
	v_pk_add_f32 v[158:159], v[110:111], v[158:159]
	s_nop 1
	v_mfma_f32_16x16x32_bf16 v[126:129], v[126:129], v[30:33], v[158:161]
	s_nop 2
	v_pk_add_f32 v[160:161], v[114:115], v[164:165]
	v_pk_add_f32 v[158:159], v[108:109], v[162:163]
	v_mfma_f32_16x16x32_bf16 v[126:129], v[134:137], v[26:29], v[126:129]
	v_pk_add_f32 v[136:137], v[106:107], v[168:169]
	v_pk_add_f32 v[134:135], v[102:103], v[166:167]
	v_mfma_f32_16x16x32_bf16 v[130:133], v[130:133], v[30:33], v[158:161]
	v_mfma_f32_16x16x32_bf16 v[130:133], v[138:141], v[26:29], v[130:133]
	s_nop 2
	v_maximum3_f32 v0, v126, v127, v128
	v_pk_add_f32 v[160:161], v[104:105], v[172:173]
	v_pk_add_f32 v[158:159], v[100:101], v[170:171]
	v_mfma_f32_16x16x32_bf16 v[134:137], v[142:145], v[22:25], v[134:137]
	v_mfma_f32_16x16x32_bf16 v[134:137], v[150:153], v[18:21], v[134:137]
	v_maximum3_f32 v138, v129, v130, v131
	v_maximum3_f32 v139, v132, v133, v133
	v_maximum3_f32 v0, v0, v138, v139
	v_mov_b32_e32 v138, v0
	s_nop 1
	v_permlane16_swap_b32_e32 v0, v138
	v_maximum3_f32 v0, v0, v138, v138
	v_mov_b32_e32 v138, v0
	s_nop 1
	v_permlane32_swap_b32_e32 v0, v138
	v_maximum3_f32 v162, v125, v0, v138
	v_mfma_f32_16x16x32_bf16 v[138:141], v[146:149], v[22:25], v[158:161]
	v_sub_f32_e32 v0, v125, v162
	v_sub_f32_e32 v125, v126, v162
	v_exp_f32_e32 v142, v125
	v_sub_f32_e32 v125, v127, v162
	v_exp_f32_e32 v144, v125
	v_sub_f32_e32 v125, v128, v162
	v_mfma_f32_16x16x32_bf16 v[138:141], v[154:157], v[18:21], v[138:141]
	v_exp_f32_e32 v146, v125
	v_sub_f32_e32 v125, v129, v162
	v_exp_f32_e32 v148, v125
	v_sub_f32_e32 v125, v130, v162
	v_exp_f32_e32 v130, v125
	v_sub_f32_e32 v125, v131, v162
	v_exp_f32_e32 v150, v125
	v_sub_f32_e32 v125, v132, v162
	v_exp_f32_e32 v132, v0
	v_sub_f32_e32 v0, v133, v162
	v_exp_f32_e32 v152, v125
	v_exp_f32_e32 v154, v0
	v_maximum3_f32 v0, v134, v135, v136
	v_maximum3_f32 v125, v137, v138, v139
	v_maximum3_f32 v129, v140, v141, v141
	v_maximum3_f32 v0, v0, v125, v129
	v_mov_b32_e32 v125, v0
	s_nop 1
	v_permlane16_swap_b32_e32 v0, v125
	v_maximum3_f32 v0, v0, v125, v125
	v_mov_b32_e32 v125, v0
	s_nop 1
	v_permlane32_swap_b32_e32 v0, v125
	v_maximum3_f32 v156, v124, v0, v125
	v_pk_mul_f32 v[56:57], v[56:57], v[132:133] op_sel_hi:[1,0]
	v_pk_mul_f32 v[54:55], v[54:55], v[132:133] op_sel_hi:[1,0]
	v_pk_mul_f32 v[64:65], v[64:65], v[132:133] op_sel_hi:[1,0]
	v_pk_mul_f32 v[62:63], v[62:63], v[132:133] op_sel_hi:[1,0]
	v_pk_mul_f32 v[60:61], v[60:61], v[132:133] op_sel_hi:[1,0]
	v_pk_mul_f32 v[58:59], v[58:59], v[132:133] op_sel_hi:[1,0]
	v_pk_mul_f32 v[52:53], v[52:53], v[132:133] op_sel_hi:[1,0]
	v_pk_mul_f32 v[50:51], v[50:51], v[132:133] op_sel_hi:[1,0]
	v_sub_f32_e32 v0, v134, v156
	v_sub_f32_e32 v133, v139, v156
	v_exp_f32_e32 v143, v0
	v_sub_f32_e32 v0, v135, v156
	v_sub_f32_e32 v131, v136, v156
	v_exp_f32_e32 v151, v133
	v_sub_f32_e32 v133, v140, v156
	v_exp_f32_e32 v145, v0
	v_sub_f32_e32 v0, v124, v156
	v_exp_f32_e32 v147, v131
	v_sub_f32_e32 v131, v137, v156
	v_exp_f32_e32 v153, v133
	v_sub_f32_e32 v133, v141, v156
	v_exp_f32_e32 v149, v131
	v_sub_f32_e32 v131, v138, v156
	v_exp_f32_e32 v155, v133
	v_exp_f32_e32 v133, v0
	v_exp_f32_e32 v131, v131
	v_cvt_pk_bf16_f32 v126, v142, v144
	v_cvt_pk_bf16_f32 v127, v146, v148
	v_cvt_pk_bf16_f32 v128, v130, v150
	v_cvt_pk_bf16_f32 v129, v152, v154
	v_mov_b32_e32 v0, v133
	v_pk_add_f32 v[124:125], v[142:143], v[144:145]
	s_setprio 1
	s_waitcnt lgkmcnt(10)
	v_mfma_f32_16x16x32_bf16 v[58:61], v[70:73], v[126:129], v[58:61]
	v_pk_mul_f32 v[48:49], v[48:49], v[0:1] op_sel_hi:[1,0]
	v_pk_mul_f32 v[46:47], v[46:47], v[0:1] op_sel_hi:[1,0]
	v_cvt_pk_bf16_f32 v70, v143, v145
	v_cvt_pk_bf16_f32 v71, v147, v149
	v_cvt_pk_bf16_f32 v72, v131, v151
	v_cvt_pk_bf16_f32 v73, v153, v155
	v_mfma_f32_16x16x32_bf16 v[54:57], v[78:81], v[126:129], v[54:57]
	v_pk_add_f32 v[78:79], v[146:147], v[124:125]
	v_pk_add_f32 v[78:79], v[148:149], v[78:79]
	s_waitcnt lgkmcnt(6)
	v_mfma_f32_16x16x32_bf16 v[46:49], v[14:17], v[70:73], v[46:49]
	v_pk_mul_f32 v[16:17], v[44:45], v[0:1] op_sel_hi:[1,0]
	v_pk_mul_f32 v[14:15], v[42:43], v[0:1] op_sel_hi:[1,0]
	v_mfma_f32_16x16x32_bf16 v[62:65], v[74:77], v[126:129], v[62:65]
	v_pk_add_f32 v[74:75], v[130:131], v[78:79]
	v_pk_add_f32 v[74:75], v[150:151], v[74:75]
	s_waitcnt lgkmcnt(4)
	v_mfma_f32_16x16x32_bf16 v[42:45], v[10:13], v[70:73], v[14:17]
	v_pk_mul_f32 v[12:13], v[40:41], v[0:1] op_sel_hi:[1,0]
	v_pk_mul_f32 v[10:11], v[38:39], v[0:1] op_sel_hi:[1,0]
	v_mfma_f32_16x16x32_bf16 v[50:53], v[66:69], v[126:129], v[50:53]
	v_pk_add_f32 v[66:67], v[152:153], v[74:75]
	v_pk_add_f32 v[14:15], v[154:155], v[66:67]
	s_waitcnt lgkmcnt(2)
	v_mfma_f32_16x16x32_bf16 v[38:41], v[6:9], v[70:73], v[10:13]
	v_pk_mul_f32 v[8:9], v[36:37], v[0:1] op_sel_hi:[1,0]
	v_pk_mul_f32 v[6:7], v[34:35], v[0:1] op_sel_hi:[1,0]
	v_pk_fma_f32 v[98:99], v[98:99], v[132:133], v[14:15]
	s_waitcnt lgkmcnt(0)
	v_mfma_f32_16x16x32_bf16 v[34:37], v[2:5], v[70:73], v[6:9]
	s_setprio 0
	v_mov_b32_e32 v125, v162
	v_mov_b32_e32 v124, v156
	s_cmp_eq_u32 s41, 2
	s_cbranch_scc1 .LBB0_281

; #define LAS __attribute__((address_space(3)))
; template <int MODE> ...
;     ...
;             if (MODE == 1) { const int ks = ktok0 + 64 * t + 32 * hf;
;                 if (ks + 31 < qtok0 - 128 || ks > qtok0 + 31 + 128) continue; }
;             bf16x8 kf[2][2][2];
; #pragma unroll
;             for (int jj = 0; jj < 2; ++jj)
; #pragma unroll
;                 for (int kt = 0; kt < 2; ++kt)
; #pragma unroll
;                     for (int ks = 0; ks < 2; ++ks) kf[jj][kt][ks] = *(const LAS bf16x8*)(Sl + kad[jj][ks] + (32 * hf + 16 * kt) * 128);
;             f32x4 bb[2][2];
; #pragma unroll
;             for (int jj = 0; jj < 2; ++jj) { const LAS f32x4* bl = bcp + ((MODE == 0) ? (dr0 + t - act0) * 8 : 16 * t + 8 * hf) + bofs[jj];
; #pragma unroll
;                 for (int kt = 0; kt < 2; ++kt) bb[jj][kt] = bl[4 * kt]; }
;             s16x4 vlo[2][4], vhi[2][4];
; #pragma unroll
;             for (int jj = 0; jj < 2; ++jj)
; #pragma unroll
;                 for (int dt = 0; dt < 4; ++dt) { const LAS unsigned char* vp = Sl + vad[jj] + (32 * hf) * 128 + ((dt ^ sv) << 5);
;                     vlo[jj][dt] = __builtin_bit_cast(s16x4, __builtin_amdgcn_ds_read_tr16_b64_v4i16((LAS s16x4*)(vp)));
;                     vhi[jj][dt] = __builtin_bit_cast(s16x4, __builtin_amdgcn_ds_read_tr16_b64_v4i16((LAS s16x4*)(vp + 2048))); }
;             __builtin_amdgcn_sched_barrier(0);
;             f32x4 s[2][2];
; #pragma unroll
;             for (int jj = 0; jj < 2; ++jj)
; #pragma unroll
;                 for (int kt = 0; kt < 2; ++kt) { f32x4 a = (MODE == 0) ? bb[jj][kt] + mneg[jj][kt] : bb[jj][kt];
;                     a = __builtin_amdgcn_mfma_f32_16x16x32_bf16(kf[jj][kt][0], qf[jj][0], a, 0, 0, 0);
;                     s[jj][kt] = __builtin_amdgcn_mfma_f32_16x16x32_bf16(kf[jj][kt][1], qf[jj][1], a, 0, 0, 0); }
;             u32x4 pw[2];
; #pragma unroll
;             for (int jj = 0; jj < 2; ++jj) {
;                 const float tm = vmax3(vmax3(s[jj][0][0], s[jj][0][1], s[jj][0][2]), vmax3(s[jj][0][3], s[jj][1][0], s[jj][1][1]), vmax3(s[jj][1][2], s[jj][1][3], s[jj][1][3]));
;                 const float mn = quad_max3(mrun[jj], tm);
;                 const float alpha = __builtin_amdgcn_exp2f(mrun[jj] - mn);
;                 mrun[jj] = mn;
;                 float rsum = 0.f;
; #pragma unroll
;                 for (int kt = 0; kt < 2; ++kt)
; #pragma unroll
.LBB0_343:
	s_add_i32 s0, s86, s65
	s_mul_hi_i32 s14, s0, 0x55555556
	s_lshr_b32 s15, s14, 31
	s_add_i32 s14, s14, s15
	s_mul_i32 s14, s14, 3
	s_sub_i32 s0, s0, s14
	s_lshl_b32 s0, s0, 14
	s_add_i32 s0, s0, 0
	s_add_i32 s14, s27, 31
	s_cmp_lt_i32 s14, s41
	s_cselect_b64 s[50:51], -1, 0
	s_cmp_gt_i32 s27, s45
	s_cselect_b64 s[52:53], -1, 0
	s_or_b64 s[50:51], s[50:51], s[52:53]
	v_add_u32_e32 v0, s0, v78
	s_and_b64 vcc, exec, s[50:51]
	v_add_u32_e32 v98, s0, v70
	v_add_u32_e32 v97, s0, v71
	v_add_u32_e32 v96, s40, v80
	v_add_u32_e32 v85, s40, v79
	v_add_u32_e32 v84, v0, v74
	v_add_u32_e32 v83, v0, v75
	v_add_u32_e32 v81, v0, v76
	v_add_u32_e32 v0, v0, v77
	s_cbranch_vccnz .LBB0_345
	v_add_u32_e32 v2, 0x10000, v96
	v_add_u32_e32 v3, 0x10040, v96
	ds_read_b128 v[100:103], v98
	ds_read_b128 v[104:107], v98 offset:2048
	ds_read_b128 v[108:111], v97
	ds_read_b128 v[112:115], v97 offset:2048
	ds_read_b128 v[118:121], v2
	ds_read_b128 v[122:125], v3
	v_add_u32_e32 v2, 0x10000, v85
	v_add_u32_e32 v3, 0x10040, v85
	ds_read_b128 v[126:129], v2
	ds_read_b128 v[130:133], v3
	ds_read_b64_tr_b16 v[14:15], v84 offset:8192
	ds_read_b64_tr_b16 v[16:17], v84 offset:10240
	ds_read_b64_tr_b16 v[10:11], v83 offset:8192
	ds_read_b64_tr_b16 v[12:13], v83 offset:10240
	ds_read_b64_tr_b16 v[6:7], v81 offset:8192
	ds_read_b64_tr_b16 v[8:9], v81 offset:10240
	ds_read_b64_tr_b16 v[2:3], v0 offset:8192
	ds_read_b64_tr_b16 v[4:5], v0 offset:10240
	s_waitcnt lgkmcnt(11)
	v_mfma_f32_16x16x32_bf16 v[118:121], v[100:103], v[30:33], v[118:121]
	s_waitcnt lgkmcnt(10)
	v_mfma_f32_16x16x32_bf16 v[122:125], v[104:107], v[30:33], v[122:125]
	v_mfma_f32_16x16x32_bf16 v[118:121], v[108:111], v[26:29], v[118:121]
	v_mfma_f32_16x16x32_bf16 v[122:125], v[112:115], v[26:29], v[122:125]
	s_waitcnt lgkmcnt(9)
	v_mfma_f32_16x16x32_bf16 v[100:103], v[100:103], v[22:25], v[126:129]
	s_nop 4
	v_maximum3_f32 v99, v118, v119, v120
	v_mfma_f32_16x16x32_bf16 v[100:103], v[108:111], v[18:21], v[100:103]
	v_maximum3_f32 v108, v121, v122, v123
	v_maximum3_f32 v109, v124, v125, v125
	v_maximum3_f32 v99, v99, v108, v109
	s_waitcnt lgkmcnt(8)
	v_mfma_f32_16x16x32_bf16 v[104:107], v[104:107], v[22:25], v[130:133]
	v_mov_b32_e32 v108, v99
	s_nop 1
	v_permlane16_swap_b32_e32 v99, v108
	v_maximum3_f32 v99, v99, v108, v108
	v_mfma_f32_16x16x32_bf16 v[104:107], v[112:115], v[18:21], v[104:107]
	v_mov_b32_e32 v108, v99
	s_nop 1
	v_permlane32_swap_b32_e32 v99, v108
	v_maximum3_f32 v99, v82, v99, v108
	v_sub_f32_e32 v82, v82, v99
	v_exp_f32_e32 v130, v82
	v_maximum3_f32 v82, v100, v101, v102
	v_maximum3_f32 v113, v103, v104, v105
	v_maximum3_f32 v115, v106, v107, v107
	v_maximum3_f32 v82, v82, v113, v115
	v_mov_b32_e32 v113, v82
	s_nop 1
	v_permlane16_swap_b32_e32 v82, v113
	v_maximum3_f32 v82, v82, v113, v113
	v_mov_b32_e32 v113, v82
	s_nop 1
	v_permlane32_swap_b32_e32 v82, v113
	v_maximum3_f32 v117, v95, v82, v113
	v_sub_f32_e32 v108, v118, v99
	v_sub_f32_e32 v82, v95, v117
	v_sub_f32_e32 v95, v100, v117
	v_exp_f32_e32 v112, v108
	v_sub_f32_e32 v108, v119, v99
	v_exp_f32_e32 v113, v95
	v_sub_f32_e32 v95, v101, v117
	v_exp_f32_e32 v114, v108
	v_sub_f32_e32 v108, v120, v99
	v_exp_f32_e32 v115, v95
	v_sub_f32_e32 v95, v102, v117
	v_exp_f32_e32 v118, v108
	v_sub_f32_e32 v108, v121, v99
	v_exp_f32_e32 v119, v95
	v_sub_f32_e32 v95, v103, v117
	v_exp_f32_e32 v120, v108
	v_sub_f32_e32 v108, v122, v99
	v_exp_f32_e32 v121, v95
	v_sub_f32_e32 v95, v104, v117
	v_exp_f32_e32 v122, v108
	v_sub_f32_e32 v108, v123, v99
	v_exp_f32_e32 v123, v95
	v_sub_f32_e32 v95, v105, v117
	v_exp_f32_e32 v126, v108
	v_sub_f32_e32 v108, v124, v99
	v_exp_f32_e32 v127, v95
	v_sub_f32_e32 v95, v106, v117
	v_pk_add_f32 v[100:101], v[112:113], v[114:115]
	v_exp_f32_e32 v124, v108
	v_sub_f32_e32 v108, v125, v99
	v_exp_f32_e32 v125, v95
	v_sub_f32_e32 v95, v107, v117
	v_pk_add_f32 v[100:101], v[118:119], v[100:101]
	v_exp_f32_e32 v128, v108
	v_pk_mul_f32 v[52:53], v[52:53], v[130:131] op_sel_hi:[1,0]
	v_pk_mul_f32 v[50:51], v[50:51], v[130:131] op_sel_hi:[1,0]
	v_pk_mul_f32 v[56:57], v[56:57], v[130:131] op_sel_hi:[1,0]
	v_pk_mul_f32 v[54:55], v[54:55], v[130:131] op_sel_hi:[1,0]
	v_pk_mul_f32 v[60:61], v[60:61], v[130:131] op_sel_hi:[1,0]
	v_pk_mul_f32 v[58:59], v[58:59], v[130:131] op_sel_hi:[1,0]
	v_pk_mul_f32 v[64:65], v[64:65], v[130:131] op_sel_hi:[1,0]
	v_pk_mul_f32 v[62:63], v[62:63], v[130:131] op_sel_hi:[1,0]
	v_exp_f32_e32 v129, v95
	v_pk_add_f32 v[100:101], v[120:121], v[100:101]
	v_exp_f32_e32 v131, v82
	v_pk_add_f32 v[100:101], v[122:123], v[100:101]
	v_cvt_pk_bf16_f32 v108, v112, v114
	v_pk_add_f32 v[100:101], v[126:127], v[100:101]
	v_pk_add_f32 v[100:101], v[124:125], v[100:101]
	v_cvt_pk_bf16_f32 v109, v118, v120
	v_pk_add_f32 v[100:101], v[128:129], v[100:101]
	v_cvt_pk_bf16_f32 v110, v122, v126
	v_cvt_pk_bf16_f32 v111, v124, v128
	v_pk_fma_f32 v[88:89], v[88:89], v[130:131], v[100:101]
	v_pk_mul_f32 v[36:37], v[36:37], v[130:131] op_sel:[0,1] op_sel_hi:[1,1]
	v_pk_mul_f32 v[34:35], v[34:35], v[130:131] op_sel:[0,1] op_sel_hi:[1,1]
	v_pk_mul_f32 v[40:41], v[40:41], v[130:131] op_sel:[0,1] op_sel_hi:[1,1]
	v_pk_mul_f32 v[38:39], v[38:39], v[130:131] op_sel:[0,1] op_sel_hi:[1,1]
	v_pk_mul_f32 v[44:45], v[44:45], v[130:131] op_sel:[0,1] op_sel_hi:[1,1]
	v_pk_mul_f32 v[42:43], v[42:43], v[130:131] op_sel:[0,1] op_sel_hi:[1,1]
	v_pk_mul_f32 v[48:49], v[48:49], v[130:131] op_sel:[0,1] op_sel_hi:[1,1]
	v_pk_mul_f32 v[46:47], v[46:47], v[130:131] op_sel:[0,1] op_sel_hi:[1,1]
	v_cvt_pk_bf16_f32 v100, v113, v115
	v_cvt_pk_bf16_f32 v101, v119, v121
	v_cvt_pk_bf16_f32 v102, v123, v127
	v_cvt_pk_bf16_f32 v103, v125, v129
	s_setprio 1
	s_waitcnt lgkmcnt(6)
	v_mfma_f32_16x16x32_bf16 v[50:53], v[14:17], v[108:111], v[50:53]
	s_waitcnt lgkmcnt(4)
	v_mfma_f32_16x16x32_bf16 v[54:57], v[10:13], v[108:111], v[54:57]
	s_waitcnt lgkmcnt(2)
	v_mfma_f32_16x16x32_bf16 v[58:61], v[6:9], v[108:111], v[58:61]
	s_waitcnt lgkmcnt(0)
	v_mfma_f32_16x16x32_bf16 v[62:65], v[2:5], v[108:111], v[62:65]
	v_mfma_f32_16x16x32_bf16 v[34:37], v[14:17], v[100:103], v[34:37]
	v_mfma_f32_16x16x32_bf16 v[38:41], v[10:13], v[100:103], v[38:41]
	v_mfma_f32_16x16x32_bf16 v[42:45], v[6:9], v[100:103], v[42:45]
	v_mfma_f32_16x16x32_bf16 v[46:49], v[2:5], v[100:103], v[46:49]
	s_setprio 0
	v_mov_b32_e32 v82, v99
	v_mov_b32_e32 v95, v117
; #define LAS __attribute__((address_space(3)))
; template <int MODE> ...
;     ...
;             if (MODE == 1) { const int ks = ktok0 + 64 * t + 32 * hf;
;                 if (ks + 31 < qtok0 - 128 || ks > qtok0 + 31 + 128) continue; }
;             bf16x8 kf[2][2][2];
; #pragma unroll
;             for (int jj = 0; jj < 2; ++jj)
; #pragma unroll
;                 for (int kt = 0; kt < 2; ++kt)
; #pragma unroll
;                     for (int ks = 0; ks < 2; ++ks) kf[jj][kt][ks] = *(const LAS bf16x8*)(Sl + kad[jj][ks] + (32 * hf + 16 * kt) * 128);
;             f32x4 bb[2][2];
; #pragma unroll
;             for (int jj = 0; jj < 2; ++jj) { const LAS f32x4* bl = bcp + ((MODE == 0) ? (dr0 + t - act0) * 8 : 16 * t + 8 * hf) + bofs[jj];
; #pragma unroll
;                 for (int kt = 0; kt < 2; ++kt) bb[jj][kt] = bl[4 * kt]; }
;             s16x4 vlo[2][4], vhi[2][4];
; #pragma unroll
;             for (int jj = 0; jj < 2; ++jj)
; #pragma unroll
;                 for (int dt = 0; dt < 4; ++dt) { const LAS unsigned char* vp = Sl + vad[jj] + (32 * hf) * 128 + ((dt ^ sv) << 5);
;                     vlo[jj][dt] = __builtin_bit_cast(s16x4, __builtin_amdgcn_ds_read_tr16_b64_v4i16((LAS s16x4*)(vp)));
;                     vhi[jj][dt] = __builtin_bit_cast(s16x4, __builtin_amdgcn_ds_read_tr16_b64_v4i16((LAS s16x4*)(vp + 2048))); }
;             __builtin_amdgcn_sched_barrier(0);
;             f32x4 s[2][2];
; #pragma unroll
;             for (int jj = 0; jj < 2; ++jj)
; #pragma unroll
;                 for (int kt = 0; kt < 2; ++kt) { f32x4 a = (MODE == 0) ? bb[jj][kt] + mneg[jj][kt] : bb[jj][kt];
;                     a = __builtin_amdgcn_mfma_f32_16x16x32_bf16(kf[jj][kt][0], qf[jj][0], a, 0, 0, 0);
;                     s[jj][kt] = __builtin_amdgcn_mfma_f32_16x16x32_bf16(kf[jj][kt][1], qf[jj][1], a, 0, 0, 0); }
;             u32x4 pw[2];
; #pragma unroll
;             for (int jj = 0; jj < 2; ++jj) {
;                 const float tm = vmax3(vmax3(s[jj][0][0], s[jj][0][1], s[jj][0][2]), vmax3(s[jj][0][3], s[jj][1][0], s[jj][1][1]), vmax3(s[jj][1][2], s[jj][1][3], s[jj][1][3]));
;                 const float mn = quad_max3(mrun[jj], tm);
;                 const float alpha = __builtin_amdgcn_exp2f(mrun[jj] - mn);
;                 mrun[jj] = mn;
;                 float rsum = 0.f;
; #pragma unroll
;                 for (int kt = 0; kt < 2; ++kt)
; #pragma unroll
.LBB0_345:
	s_add_i32 s0, s27, 32
	s_add_i32 s14, s27, 63
	s_cmp_lt_i32 s14, s41
	s_cselect_b64 s[50:51], -1, 0
	s_cmp_gt_i32 s0, s45
	s_cselect_b64 s[52:53], -1, 0
	s_or_b64 s[50:51], s[50:51], s[52:53]
	s_and_b64 vcc, exec, s[50:51]
	s_cbranch_vccnz .LBB0_333
	v_add_u32_e32 v2, 0x10080, v96
	v_add_u32_e32 v3, 0x100c0, v96
	ds_read_b128 v[100:103], v98 offset:4096
	ds_read_b128 v[104:107], v98 offset:6144
	ds_read_b128 v[108:111], v97 offset:4096
	ds_read_b128 v[112:115], v97 offset:6144
	ds_read_b128 v[96:99], v2
	ds_read_b128 v[118:121], v3
	v_add_u32_e32 v2, 0x10080, v85
	v_add_u32_e32 v3, 0x100c0, v85
	ds_read_b128 v[122:125], v2
	ds_read_b128 v[126:129], v3
	ds_read_b64_tr_b16 v[14:15], v84 offset:12288
	ds_read_b64_tr_b16 v[16:17], v84 offset:14336
	ds_read_b64_tr_b16 v[10:11], v83 offset:12288
	ds_read_b64_tr_b16 v[12:13], v83 offset:14336
	ds_read_b64_tr_b16 v[6:7], v81 offset:12288
	ds_read_b64_tr_b16 v[8:9], v81 offset:14336
	ds_read_b64_tr_b16 v[2:3], v0 offset:12288
	ds_read_b64_tr_b16 v[4:5], v0 offset:14336
	s_waitcnt lgkmcnt(11)
	v_mfma_f32_16x16x32_bf16 v[96:99], v[100:103], v[30:33], v[96:99]
	s_waitcnt lgkmcnt(10)
	v_mfma_f32_16x16x32_bf16 v[118:121], v[104:107], v[30:33], v[118:121]
	v_mfma_f32_16x16x32_bf16 v[96:99], v[108:111], v[26:29], v[96:99]
	v_mfma_f32_16x16x32_bf16 v[118:121], v[112:115], v[26:29], v[118:121]
	s_waitcnt lgkmcnt(9)
	v_mfma_f32_16x16x32_bf16 v[100:103], v[100:103], v[22:25], v[122:125]
	s_nop 4
	v_maximum3_f32 v0, v96, v97, v98
	v_maximum3_f32 v81, v99, v118, v119
	v_maximum3_f32 v83, v120, v121, v121
	v_maximum3_f32 v0, v0, v81, v83
	v_mov_b32_e32 v81, v0
	s_waitcnt lgkmcnt(8)
	v_mfma_f32_16x16x32_bf16 v[104:107], v[104:107], v[22:25], v[126:129]
	v_permlane16_swap_b32_e32 v0, v81
	v_maximum3_f32 v0, v0, v81, v81
	v_mov_b32_e32 v81, v0
	s_nop 1
	v_permlane32_swap_b32_e32 v0, v81
	v_mfma_f32_16x16x32_bf16 v[100:103], v[108:111], v[18:21], v[100:103]
	v_maximum3_f32 v81, v82, v0, v81
	v_sub_f32_e32 v0, v82, v81
	v_sub_f32_e32 v82, v96, v81
	v_mfma_f32_16x16x32_bf16 v[104:107], v[112:115], v[18:21], v[104:107]
	v_exp_f32_e32 v96, v82
	v_sub_f32_e32 v82, v97, v81
	v_exp_f32_e32 v108, v82
	v_sub_f32_e32 v82, v98, v81
	v_exp_f32_e32 v98, v82
	v_sub_f32_e32 v82, v99, v81
	v_exp_f32_e32 v122, v0
	v_maximum3_f32 v0, v100, v101, v102
	v_maximum3_f32 v97, v103, v104, v105
	v_maximum3_f32 v99, v106, v107, v107
	v_maximum3_f32 v0, v0, v97, v99
	v_mov_b32_e32 v97, v0
	s_nop 1
	v_permlane16_swap_b32_e32 v0, v97
	v_maximum3_f32 v0, v0, v97, v97
	v_mov_b32_e32 v97, v0
	s_nop 1
	v_permlane32_swap_b32_e32 v0, v97
	v_maximum3_f32 v117, v95, v0, v97
	v_sub_f32_e32 v0, v95, v117
	v_sub_f32_e32 v95, v100, v117
	v_exp_f32_e32 v97, v95
	v_sub_f32_e32 v95, v101, v117
	v_exp_f32_e32 v109, v95
	v_sub_f32_e32 v95, v102, v117
	v_exp_f32_e32 v99, v95
	v_sub_f32_e32 v95, v103, v117
	v_exp_f32_e32 v110, v82
	v_sub_f32_e32 v82, v118, v81
	v_exp_f32_e32 v111, v95
	v_sub_f32_e32 v95, v104, v117
	v_exp_f32_e32 v112, v82
	v_sub_f32_e32 v82, v119, v81
	v_exp_f32_e32 v113, v95
	v_sub_f32_e32 v95, v105, v117
	v_exp_f32_e32 v114, v82
	v_sub_f32_e32 v82, v120, v81
	v_exp_f32_e32 v115, v95
	v_sub_f32_e32 v95, v106, v117
	v_exp_f32_e32 v118, v82
	v_sub_f32_e32 v82, v121, v81
	v_pk_mul_f32 v[52:53], v[52:53], v[122:123] op_sel_hi:[1,0]
	v_pk_mul_f32 v[50:51], v[50:51], v[122:123] op_sel_hi:[1,0]
	v_pk_mul_f32 v[56:57], v[56:57], v[122:123] op_sel_hi:[1,0]
	v_pk_mul_f32 v[54:55], v[54:55], v[122:123] op_sel_hi:[1,0]
	v_pk_mul_f32 v[60:61], v[60:61], v[122:123] op_sel_hi:[1,0]
	v_pk_mul_f32 v[58:59], v[58:59], v[122:123] op_sel_hi:[1,0]
	v_pk_mul_f32 v[64:65], v[64:65], v[122:123] op_sel_hi:[1,0]
	v_pk_mul_f32 v[62:63], v[62:63], v[122:123] op_sel_hi:[1,0]
	v_exp_f32_e32 v119, v95
	v_sub_f32_e32 v95, v107, v117
	v_exp_f32_e32 v123, v0
	v_exp_f32_e32 v120, v82
	v_exp_f32_e32 v121, v95
	v_pk_add_f32 v[100:101], v[96:97], v[108:109]
	v_mov_b32_e32 v0, v123
	v_pk_add_f32 v[100:101], v[98:99], v[100:101]
	v_cvt_pk_bf16_f32 v82, v96, v108
	v_pk_add_f32 v[100:101], v[110:111], v[100:101]
	v_cvt_pk_bf16_f32 v83, v98, v110
	v_cvt_pk_bf16_f32 v84, v112, v114
	v_cvt_pk_bf16_f32 v85, v118, v120
	v_pk_add_f32 v[100:101], v[112:113], v[100:101]
	v_pk_mul_f32 v[36:37], v[36:37], v[0:1] op_sel_hi:[1,0]
	v_pk_mul_f32 v[34:35], v[34:35], v[0:1] op_sel_hi:[1,0]
	v_pk_mul_f32 v[40:41], v[40:41], v[0:1] op_sel_hi:[1,0]
	v_pk_mul_f32 v[38:39], v[38:39], v[0:1] op_sel_hi:[1,0]
	v_pk_mul_f32 v[44:45], v[44:45], v[0:1] op_sel_hi:[1,0]
	v_pk_mul_f32 v[42:43], v[42:43], v[0:1] op_sel_hi:[1,0]
	v_pk_mul_f32 v[48:49], v[48:49], v[0:1] op_sel_hi:[1,0]
	v_pk_mul_f32 v[46:47], v[46:47], v[0:1] op_sel_hi:[1,0]
	v_cvt_pk_bf16_f32 v96, v97, v109
	v_cvt_pk_bf16_f32 v97, v99, v111
	v_cvt_pk_bf16_f32 v98, v113, v115
	v_cvt_pk_bf16_f32 v99, v119, v121
	v_pk_add_f32 v[100:101], v[114:115], v[100:101]
	s_setprio 1
	s_waitcnt lgkmcnt(6)
	v_mfma_f32_16x16x32_bf16 v[50:53], v[14:17], v[82:85], v[50:53]
	v_pk_add_f32 v[100:101], v[118:119], v[100:101]
	v_pk_add_f32 v[100:101], v[120:121], v[100:101]
	s_waitcnt lgkmcnt(4)
	v_mfma_f32_16x16x32_bf16 v[54:57], v[10:13], v[82:85], v[54:57]
	v_fma_f32 v88, v88, v122, v100
	v_fma_f32 v89, v89, v123, v101
	s_waitcnt lgkmcnt(2)
	v_mfma_f32_16x16x32_bf16 v[58:61], v[6:9], v[82:85], v[58:61]
	s_waitcnt lgkmcnt(0)
	v_mfma_f32_16x16x32_bf16 v[62:65], v[2:5], v[82:85], v[62:65]
	v_mfma_f32_16x16x32_bf16 v[34:37], v[14:17], v[96:99], v[34:37]
	v_mfma_f32_16x16x32_bf16 v[38:41], v[10:13], v[96:99], v[38:41]
	v_mfma_f32_16x16x32_bf16 v[42:45], v[6:9], v[96:99], v[42:45]
	v_mfma_f32_16x16x32_bf16 v[46:49], v[2:5], v[96:99], v[46:49]
	s_setprio 0
	v_mov_b32_e32 v95, v117
	v_mov_b32_e32 v82, v81
	s_branch .LBB0_333

; #define LAS __attribute__((address_space(3)))
; template <int MODE> ...
;     ...
;             if (MODE == 1) { const int ks = ktok0 + 64 * t + 32 * hf;
;                 if (ks + 31 < qtok0 - 128 || ks > qtok0 + 31 + 128) continue; }
;             bf16x8 kf[2][2][2];
; #pragma unroll
;             for (int jj = 0; jj < 2; ++jj)
; #pragma unroll
;                 for (int kt = 0; kt < 2; ++kt)
; #pragma unroll
;                     for (int ks = 0; ks < 2; ++ks) kf[jj][kt][ks] = *(const LAS bf16x8*)(Sl + kad[jj][ks] + (32 * hf + 16 * kt) * 128);
;             f32x4 bb[2][2];
; #pragma unroll
;             for (int jj = 0; jj < 2; ++jj) { const LAS f32x4* bl = bcp + ((MODE == 0) ? (dr0 + t - act0) * 8 : 16 * t + 8 * hf) + bofs[jj];
; #pragma unroll
;                 for (int kt = 0; kt < 2; ++kt) bb[jj][kt] = bl[4 * kt]; }
;             s16x4 vlo[2][4], vhi[2][4];
; #pragma unroll
;             for (int jj = 0; jj < 2; ++jj)
; #pragma unroll
;                 for (int dt = 0; dt < 4; ++dt) { const LAS unsigned char* vp = Sl + vad[jj] + (32 * hf) * 128 + ((dt ^ sv) << 5);
;                     vlo[jj][dt] = __builtin_bit_cast(s16x4, __builtin_amdgcn_ds_read_tr16_b64_v4i16((LAS s16x4*)(vp)));
;                     vhi[jj][dt] = __builtin_bit_cast(s16x4, __builtin_amdgcn_ds_read_tr16_b64_v4i16((LAS s16x4*)(vp + 2048))); }
;             __builtin_amdgcn_sched_barrier(0);
;             f32x4 s[2][2];
; #pragma unroll
;             for (int jj = 0; jj < 2; ++jj)
; #pragma unroll
;                 for (int kt = 0; kt < 2; ++kt) { f32x4 a = (MODE == 0) ? bb[jj][kt] + mneg[jj][kt] : bb[jj][kt];
;                     a = __builtin_amdgcn_mfma_f32_16x16x32_bf16(kf[jj][kt][0], qf[jj][0], a, 0, 0, 0);
;                     s[jj][kt] = __builtin_amdgcn_mfma_f32_16x16x32_bf16(kf[jj][kt][1], qf[jj][1], a, 0, 0, 0); }
;             u32x4 pw[2];
; #pragma unroll
;             for (int jj = 0; jj < 2; ++jj) {
;                 const float tm = vmax3(vmax3(s[jj][0][0], s[jj][0][1], s[jj][0][2]), vmax3(s[jj][0][3], s[jj][1][0], s[jj][1][1]), vmax3(s[jj][1][2], s[jj][1][3], s[jj][1][3]));
;                 const float mn = quad_max3(mrun[jj], tm);
;                 const float alpha = __builtin_amdgcn_exp2f(mrun[jj] - mn);
;                 mrun[jj] = mn;
;                 float rsum = 0.f;
; #pragma unroll
;                 for (int kt = 0; kt < 2; ++kt)
; #pragma unroll
.LBB0_356:
	v_lshl_add_u64 v[6:7], v[66:67], 1, s[38:39]
	global_load_dwordx4 v[2:5], v[6:7], off
	global_load_dwordx4 v[10:13], v[6:7], off offset:64
	v_add_co_u32_e32 v6, vcc, 0x12000, v6
	s_cmp_lt_i32 s5, 1
	s_nop 0
	v_addc_co_u32_e32 v7, vcc, 0, v7, vcc
	global_load_dwordx4 v[14:17], v[6:7], off
	s_nop 0
	global_load_dwordx4 v[6:9], v[6:7], off offset:64
	s_cbranch_scc1 .LBB0_361
	s_mul_i32 s0, s22, 0x600
	s_add_i32 s27, s0, 0
	s_add_i32 s0, s26, s86
	s_mul_hi_i32 s14, s0, 0x55555556
	s_lshr_b32 s15, s14, 31
	s_add_i32 s14, s14, s15
	s_mul_i32 s14, s14, 3
	s_sub_i32 s0, s0, s14
	s_lshl_b32 s30, s26, 6
	s_lshl_b32 s0, s0, 14
	s_add_i32 s14, s30, s24
	s_add_i32 s27, s27, 0x10000
	s_add_i32 s0, s0, 0
	s_lshl_b32 s26, s26, 8
	s_or_b32 s15, s14, 31
	s_add_i32 s31, s25, 0xffffff80
	s_cmp_lt_i32 s15, s31
	s_cselect_b64 s[38:39], -1, 0
	s_addk_i32 s25, 0x9f
	s_cmp_gt_i32 s14, s25
	s_cselect_b64 s[40:41], -1, 0
	s_or_b64 s[38:39], s[38:39], s[40:41]
	v_add_u32_e32 v100, s0, v70
	v_add_u32_e32 v99, s0, v71
	v_add3_u32 v66, v72, v73, s0
	s_movk_i32 s0, 0x60
	s_and_b64 vcc, exec, s[38:39]
	v_add_u32_e32 v98, v66, v74
	v_xad_u32 v97, v74, 32, v66
	v_xad_u32 v0, v74, 64, v66
	v_xad_u32 v96, v74, s0, v66
	s_cbranch_vccnz .LBB0_359
	s_add_i32 s0, s27, s26
	v_lshl_add_u32 v66, v93, 4, s0
	ds_read_b128 v[102:105], v100
	ds_read_b128 v[106:109], v100 offset:2048
	ds_read_b128 v[110:113], v99
	ds_read_b128 v[118:121], v99 offset:2048
	ds_read_b128 v[122:125], v66
	ds_read_b128 v[126:129], v66 offset:64
	v_lshl_add_u32 v66, v94, 4, s0
	ds_read_b128 v[130:133], v66
	ds_read_b128 v[134:137], v66 offset:64
	ds_read_b64_tr_b16 v[78:79], v98 offset:8192
	ds_read_b64_tr_b16 v[80:81], v98 offset:10240
	ds_read_b64_tr_b16 v[74:75], v97 offset:8192
	ds_read_b64_tr_b16 v[76:77], v97 offset:10240
	ds_read_b64_tr_b16 v[70:71], v0 offset:8192
	ds_read_b64_tr_b16 v[72:73], v0 offset:10240
	ds_read_b64_tr_b16 v[66:67], v96 offset:8192
	ds_read_b64_tr_b16 v[68:69], v96 offset:10240
	s_waitcnt lgkmcnt(11)
	v_mfma_f32_16x16x32_bf16 v[122:125], v[102:105], v[30:33], v[122:125]
	s_waitcnt lgkmcnt(10)
	v_mfma_f32_16x16x32_bf16 v[126:129], v[106:109], v[30:33], v[126:129]
	s_waitcnt lgkmcnt(9)
	v_mfma_f32_16x16x32_bf16 v[102:105], v[102:105], v[22:25], v[130:133]
	s_waitcnt lgkmcnt(8)
	v_mfma_f32_16x16x32_bf16 v[106:109], v[106:109], v[22:25], v[134:137]
	v_mfma_f32_16x16x32_bf16 v[102:105], v[110:113], v[18:21], v[102:105]
	v_mfma_f32_16x16x32_bf16 v[106:109], v[118:121], v[18:21], v[106:109]
	v_mfma_f32_16x16x32_bf16 v[122:125], v[110:113], v[26:29], v[122:125]
	s_nop 5
	v_maximum3_f32 v111, v102, v103, v104
	v_maximum3_f32 v113, v105, v106, v107
	v_maximum3_f32 v115, v108, v109, v109
	v_mfma_f32_16x16x32_bf16 v[126:129], v[118:121], v[26:29], v[126:129]
	v_maximum3_f32 v111, v111, v113, v115
	v_maximum3_f32 v83, v122, v123, v124
	v_mov_b32_e32 v113, v111
	s_nop 1
	v_permlane16_swap_b32_e32 v111, v113
	v_maximum3_f32 v111, v111, v113, v113
	s_nop 0
	v_maximum3_f32 v84, v125, v126, v127
	v_maximum3_f32 v85, v128, v129, v129
	v_maximum3_f32 v83, v83, v84, v85
	v_mov_b32_e32 v84, v83
	s_nop 1
	v_permlane16_swap_b32_e32 v83, v84
	v_maximum3_f32 v83, v83, v84, v84
	v_mov_b32_e32 v113, v111
	v_mov_b32_e32 v84, v83
	s_nop 0
	v_permlane32_swap_b32_e32 v111, v113
	v_permlane32_swap_b32_e32 v83, v84
	v_maximum3_f32 v117, v95, v111, v113
	v_maximum3_f32 v101, v82, v83, v84
	v_sub_f32_e32 v102, v102, v117
	v_sub_f32_e32 v83, v122, v101
	v_exp_f32_e32 v111, v102
	v_sub_f32_e32 v102, v103, v117
	v_exp_f32_e32 v110, v83
	v_sub_f32_e32 v83, v123, v101
	v_exp_f32_e32 v113, v102
	v_sub_f32_e32 v102, v104, v117
	v_exp_f32_e32 v112, v83
	v_sub_f32_e32 v83, v124, v101
	v_exp_f32_e32 v115, v102
	v_sub_f32_e32 v102, v105, v117
	v_exp_f32_e32 v114, v83
	v_sub_f32_e32 v83, v125, v101
	v_exp_f32_e32 v119, v102
	v_sub_f32_e32 v102, v106, v117
	v_exp_f32_e32 v118, v83
	v_sub_f32_e32 v83, v126, v101
	v_exp_f32_e32 v121, v102
	v_sub_f32_e32 v102, v107, v117
	v_sub_f32_e32 v82, v82, v101
	v_exp_f32_e32 v120, v83
	v_sub_f32_e32 v83, v127, v101
	v_exp_f32_e32 v123, v102
	v_sub_f32_e32 v102, v108, v117
	v_exp_f32_e32 v122, v83
	v_sub_f32_e32 v83, v128, v101
	v_exp_f32_e32 v128, v82
	v_pk_add_f32 v[130:131], v[110:111], 0 op_sel_hi:[1,0]
	v_exp_f32_e32 v125, v102
	v_sub_f32_e32 v102, v109, v117
	v_exp_f32_e32 v127, v102
	v_pk_add_f32 v[102:103], v[112:113], v[130:131]
	v_exp_f32_e32 v124, v83
	v_sub_f32_e32 v83, v129, v101
	v_pk_add_f32 v[102:103], v[114:115], v[102:103]
	v_exp_f32_e32 v126, v83
	v_sub_f32_e32 v95, v95, v117
	v_pk_add_f32 v[102:103], v[118:119], v[102:103]
	v_pk_mul_f32 v[52:53], v[52:53], v[128:129] op_sel_hi:[1,0]
	v_pk_mul_f32 v[50:51], v[50:51], v[128:129] op_sel_hi:[1,0]
	v_pk_mul_f32 v[56:57], v[56:57], v[128:129] op_sel_hi:[1,0]
	v_pk_mul_f32 v[54:55], v[54:55], v[128:129] op_sel_hi:[1,0]
	v_pk_mul_f32 v[60:61], v[60:61], v[128:129] op_sel_hi:[1,0]
	v_pk_mul_f32 v[58:59], v[58:59], v[128:129] op_sel_hi:[1,0]
	v_pk_mul_f32 v[64:65], v[64:65], v[128:129] op_sel_hi:[1,0]
	v_pk_mul_f32 v[62:63], v[62:63], v[128:129] op_sel_hi:[1,0]
	v_exp_f32_e32 v129, v95
	v_pk_add_f32 v[102:103], v[120:121], v[102:103]
	v_cvt_pk_bf16_f32 v82, v110, v112
	v_pk_add_f32 v[102:103], v[122:123], v[102:103]
	v_cvt_pk_bf16_f32 v83, v114, v118
	v_pk_add_f32 v[102:103], v[124:125], v[102:103]
	v_cvt_pk_bf16_f32 v84, v120, v122
	v_pk_add_f32 v[102:103], v[126:127], v[102:103]
	v_cvt_pk_bf16_f32 v85, v124, v126
	v_pk_fma_f32 v[88:89], v[88:89], v[128:129], v[102:103]
	v_pk_mul_f32 v[36:37], v[36:37], v[128:129] op_sel:[0,1] op_sel_hi:[1,1]
	v_pk_mul_f32 v[34:35], v[34:35], v[128:129] op_sel:[0,1] op_sel_hi:[1,1]
	v_pk_mul_f32 v[40:41], v[40:41], v[128:129] op_sel:[0,1] op_sel_hi:[1,1]
	v_pk_mul_f32 v[38:39], v[38:39], v[128:129] op_sel:[0,1] op_sel_hi:[1,1]
	v_pk_mul_f32 v[44:45], v[44:45], v[128:129] op_sel:[0,1] op_sel_hi:[1,1]
	v_pk_mul_f32 v[42:43], v[42:43], v[128:129] op_sel:[0,1] op_sel_hi:[1,1]
	v_pk_mul_f32 v[48:49], v[48:49], v[128:129] op_sel:[0,1] op_sel_hi:[1,1]
	v_pk_mul_f32 v[46:47], v[46:47], v[128:129] op_sel:[0,1] op_sel_hi:[1,1]
	v_cvt_pk_bf16_f32 v102, v111, v113
	v_cvt_pk_bf16_f32 v103, v115, v119
	v_cvt_pk_bf16_f32 v104, v121, v123
	v_cvt_pk_bf16_f32 v105, v125, v127
	s_setprio 1
	s_waitcnt lgkmcnt(6)
	v_mfma_f32_16x16x32_bf16 v[50:53], v[78:81], v[82:85], v[50:53]
	s_waitcnt lgkmcnt(4)
	v_mfma_f32_16x16x32_bf16 v[54:57], v[74:77], v[82:85], v[54:57]
	s_waitcnt lgkmcnt(2)
	v_mfma_f32_16x16x32_bf16 v[58:61], v[70:73], v[82:85], v[58:61]
	s_waitcnt lgkmcnt(0)
	v_mfma_f32_16x16x32_bf16 v[62:65], v[66:69], v[82:85], v[62:65]
	v_mfma_f32_16x16x32_bf16 v[34:37], v[78:81], v[102:105], v[34:37]
	v_mfma_f32_16x16x32_bf16 v[38:41], v[74:77], v[102:105], v[38:41]
	v_mfma_f32_16x16x32_bf16 v[42:45], v[70:73], v[102:105], v[42:45]
	v_mfma_f32_16x16x32_bf16 v[46:49], v[66:69], v[102:105], v[46:49]
	s_setprio 0
	v_mov_b32_e32 v82, v101
	v_mov_b32_e32 v95, v117
; #define LAS __attribute__((address_space(3)))
; template <int MODE> ...
;     ...
;             if (MODE == 1) { const int ks = ktok0 + 64 * t + 32 * hf;
;                 if (ks + 31 < qtok0 - 128 || ks > qtok0 + 31 + 128) continue; }
;             bf16x8 kf[2][2][2];
; #pragma unroll
;             for (int jj = 0; jj < 2; ++jj)
; #pragma unroll
;                 for (int kt = 0; kt < 2; ++kt)
; #pragma unroll
;                     for (int ks = 0; ks < 2; ++ks) kf[jj][kt][ks] = *(const LAS bf16x8*)(Sl + kad[jj][ks] + (32 * hf + 16 * kt) * 128);
;             f32x4 bb[2][2];
; #pragma unroll
;             for (int jj = 0; jj < 2; ++jj) { const LAS f32x4* bl = bcp + ((MODE == 0) ? (dr0 + t - act0) * 8 : 16 * t + 8 * hf) + bofs[jj];
; #pragma unroll
;                 for (int kt = 0; kt < 2; ++kt) bb[jj][kt] = bl[4 * kt]; }
;             s16x4 vlo[2][4], vhi[2][4];
; #pragma unroll
;             for (int jj = 0; jj < 2; ++jj)
; #pragma unroll
;                 for (int dt = 0; dt < 4; ++dt) { const LAS unsigned char* vp = Sl + vad[jj] + (32 * hf) * 128 + ((dt ^ sv) << 5);
;                     vlo[jj][dt] = __builtin_bit_cast(s16x4, __builtin_amdgcn_ds_read_tr16_b64_v4i16((LAS s16x4*)(vp)));
;                     vhi[jj][dt] = __builtin_bit_cast(s16x4, __builtin_amdgcn_ds_read_tr16_b64_v4i16((LAS s16x4*)(vp + 2048))); }
;             __builtin_amdgcn_sched_barrier(0);
;             f32x4 s[2][2];
; #pragma unroll
;             for (int jj = 0; jj < 2; ++jj)
; #pragma unroll
;                 for (int kt = 0; kt < 2; ++kt) { f32x4 a = (MODE == 0) ? bb[jj][kt] + mneg[jj][kt] : bb[jj][kt];
;                     a = __builtin_amdgcn_mfma_f32_16x16x32_bf16(kf[jj][kt][0], qf[jj][0], a, 0, 0, 0);
;                     s[jj][kt] = __builtin_amdgcn_mfma_f32_16x16x32_bf16(kf[jj][kt][1], qf[jj][1], a, 0, 0, 0); }
;             u32x4 pw[2];
; #pragma unroll
;             for (int jj = 0; jj < 2; ++jj) {
;                 const float tm = vmax3(vmax3(s[jj][0][0], s[jj][0][1], s[jj][0][2]), vmax3(s[jj][0][3], s[jj][1][0], s[jj][1][1]), vmax3(s[jj][1][2], s[jj][1][3], s[jj][1][3]));
;                 const float mn = quad_max3(mrun[jj], tm);
;                 const float alpha = __builtin_amdgcn_exp2f(mrun[jj] - mn);
;                 mrun[jj] = mn;
;                 float rsum = 0.f;
; #pragma unroll
;                 for (int kt = 0; kt < 2; ++kt)
; #pragma unroll
.LBB0_359:
	s_or_b32 s0, s30, 32
	s_add_i32 s0, s0, s24
	s_or_b32 s14, s0, 31
	s_cmp_lt_i32 s14, s31
	s_cselect_b64 s[30:31], -1, 0
	s_cmp_gt_i32 s0, s25
	s_cselect_b64 s[24:25], -1, 0
	s_or_b64 s[24:25], s[30:31], s[24:25]
	s_and_b64 vcc, exec, s[24:25]
	s_cbranch_vccnz .LBB0_361
	s_add_i32 s27, s27, s26
	v_lshl_add_u32 v83, v93, 4, s27
	ds_read_b128 v[66:69], v100 offset:4096
	ds_read_b128 v[70:73], v100 offset:6144
	ds_read_b128 v[74:77], v99 offset:4096
	ds_read_b128 v[78:81], v99 offset:6144
	ds_read_b128 v[100:103], v83 offset:128
	ds_read_b128 v[104:107], v83 offset:192
	v_lshl_add_u32 v83, v94, 4, s27
	ds_read_b128 v[108:111], v83 offset:128
	ds_read_b128 v[112:115], v83 offset:192
	ds_read_b64_tr_b16 v[118:119], v98 offset:12288
	ds_read_b64_tr_b16 v[120:121], v98 offset:14336
	ds_read_b64_tr_b16 v[122:123], v97 offset:12288
	ds_read_b64_tr_b16 v[124:125], v97 offset:14336
	ds_read_b64_tr_b16 v[126:127], v0 offset:12288
	ds_read_b64_tr_b16 v[128:129], v0 offset:14336
	ds_read_b64_tr_b16 v[130:131], v96 offset:12288
	ds_read_b64_tr_b16 v[132:133], v96 offset:14336
	s_waitcnt lgkmcnt(11)
	v_mfma_f32_16x16x32_bf16 v[96:99], v[66:69], v[30:33], v[100:103]
	s_waitcnt lgkmcnt(10)
	v_mfma_f32_16x16x32_bf16 v[30:33], v[70:73], v[30:33], v[104:107]
	v_mfma_f32_16x16x32_bf16 v[96:99], v[74:77], v[26:29], v[96:99]
	v_mfma_f32_16x16x32_bf16 v[26:29], v[78:81], v[26:29], v[30:33]
	s_nop 6
	v_maximum3_f32 v0, v96, v97, v98
	v_maximum3_f32 v30, v99, v26, v27
	v_maximum3_f32 v31, v28, v29, v29
	v_maximum3_f32 v0, v0, v30, v31
	v_mov_b32_e32 v30, v0
	s_nop 1
	v_permlane16_swap_b32_e32 v0, v30
	v_maximum3_f32 v0, v0, v30, v30
	v_mov_b32_e32 v30, v0
	s_nop 1
	v_permlane32_swap_b32_e32 v0, v30
	v_maximum3_f32 v0, v82, v0, v30
	s_waitcnt lgkmcnt(9)
	v_mfma_f32_16x16x32_bf16 v[30:33], v[66:69], v[22:25], v[108:111]
	v_sub_f32_e32 v83, v82, v0
	v_sub_f32_e32 v66, v97, v0
	v_exp_f32_e32 v84, v66
	s_waitcnt lgkmcnt(8)
	v_mfma_f32_16x16x32_bf16 v[22:25], v[70:73], v[22:25], v[112:115]
	v_sub_f32_e32 v66, v98, v0
	v_sub_f32_e32 v82, v96, v0
	v_sub_f32_e32 v26, v26, v0
	v_mfma_f32_16x16x32_bf16 v[30:33], v[74:77], v[18:21], v[30:33]
	v_exp_f32_e32 v74, v66
	v_sub_f32_e32 v66, v99, v0
	v_exp_f32_e32 v82, v82
	v_mfma_f32_16x16x32_bf16 v[18:21], v[78:81], v[18:21], v[22:25]
	v_exp_f32_e32 v78, v83
	v_exp_f32_e32 v70, v66
	v_exp_f32_e32 v72, v26
	v_sub_f32_e32 v22, v27, v0
	v_exp_f32_e32 v76, v22
	v_sub_f32_e32 v22, v28, v0
	v_sub_f32_e32 v0, v29, v0
	v_exp_f32_e32 v80, v22
	v_exp_f32_e32 v94, v0
	v_pk_mul_f32 v[22:23], v[50:51], v[78:79] op_sel_hi:[1,0]
	v_maximum3_f32 v0, v30, v31, v32
	v_maximum3_f32 v50, v33, v18, v19
	v_maximum3_f32 v51, v20, v21, v21
	v_maximum3_f32 v0, v0, v50, v51
	v_mov_b32_e32 v50, v0
	s_nop 1
	v_permlane16_swap_b32_e32 v0, v50
	v_maximum3_f32 v0, v0, v50, v50
	v_mov_b32_e32 v50, v0
	s_nop 1
	v_permlane32_swap_b32_e32 v0, v50
	v_maximum3_f32 v0, v95, v0, v50
	v_sub_f32_e32 v30, v30, v0
	v_exp_f32_e32 v83, v30
	v_sub_f32_e32 v30, v31, v0
	v_exp_f32_e32 v85, v30
	v_sub_f32_e32 v30, v32, v0
	v_sub_f32_e32 v18, v18, v0
	v_exp_f32_e32 v75, v30
	v_sub_f32_e32 v30, v33, v0
	v_exp_f32_e32 v73, v18
	v_sub_f32_e32 v18, v19, v0
	v_sub_f32_e32 v50, v95, v0
	v_exp_f32_e32 v71, v30
	v_exp_f32_e32 v77, v18
	v_sub_f32_e32 v18, v20, v0
	v_pk_mul_f32 v[24:25], v[52:53], v[78:79] op_sel_hi:[1,0]
	v_pk_mul_f32 v[28:29], v[56:57], v[78:79] op_sel_hi:[1,0]
	v_pk_mul_f32 v[26:27], v[54:55], v[78:79] op_sel_hi:[1,0]
	v_pk_mul_f32 v[60:61], v[60:61], v[78:79] op_sel_hi:[1,0]
	v_pk_mul_f32 v[58:59], v[58:59], v[78:79] op_sel_hi:[1,0]
	v_pk_mul_f32 v[64:65], v[64:65], v[78:79] op_sel_hi:[1,0]
	v_pk_mul_f32 v[62:63], v[62:63], v[78:79] op_sel_hi:[1,0]
	v_exp_f32_e32 v81, v18
	v_sub_f32_e32 v0, v21, v0
	v_exp_f32_e32 v79, v50
	v_exp_f32_e32 v95, v0
	v_pk_add_f32 v[18:19], v[82:83], v[84:85]
	v_cvt_pk_bf16_f32 v66, v82, v84
	v_pk_add_f32 v[18:19], v[74:75], v[18:19]
	v_cvt_pk_bf16_f32 v67, v74, v70
	v_pk_add_f32 v[18:19], v[70:71], v[18:19]
	v_cvt_pk_bf16_f32 v68, v72, v76
	v_cvt_pk_bf16_f32 v69, v80, v94
	v_pk_add_f32 v[18:19], v[72:73], v[18:19]
	v_mov_b32_e32 v0, v79
	s_setprio 1
	s_waitcnt lgkmcnt(6)
	v_mfma_f32_16x16x32_bf16 v[50:53], v[118:121], v[66:69], v[22:25]
	v_pk_mul_f32 v[20:21], v[36:37], v[0:1] op_sel_hi:[1,0]
	s_waitcnt lgkmcnt(4)
	v_mfma_f32_16x16x32_bf16 v[54:57], v[122:125], v[66:69], v[26:29]
	v_cvt_pk_bf16_f32 v22, v83, v85
	v_cvt_pk_bf16_f32 v23, v75, v71
	v_cvt_pk_bf16_f32 v24, v73, v77
	v_pk_add_f32 v[26:27], v[76:77], v[18:19]
	v_pk_mul_f32 v[18:19], v[34:35], v[0:1] op_sel_hi:[1,0]
	v_cvt_pk_bf16_f32 v25, v81, v95
	s_waitcnt lgkmcnt(2)
	v_mfma_f32_16x16x32_bf16 v[58:61], v[126:129], v[66:69], v[58:61]
	v_pk_add_f32 v[26:27], v[80:81], v[26:27]
	v_pk_add_f32 v[26:27], v[94:95], v[26:27]
	v_mfma_f32_16x16x32_bf16 v[34:37], v[118:121], v[22:25], v[18:21]
	v_fma_f32 v88, v88, v78, v26
	v_fma_f32 v89, v89, v79, v27
	s_nop 0
	v_pk_mul_f32 v[20:21], v[40:41], v[0:1] op_sel_hi:[1,0]
	v_pk_mul_f32 v[18:19], v[38:39], v[0:1] op_sel_hi:[1,0]
	s_waitcnt lgkmcnt(0)
	v_mfma_f32_16x16x32_bf16 v[62:65], v[130:133], v[66:69], v[62:65]
	v_mfma_f32_16x16x32_bf16 v[38:41], v[122:125], v[22:25], v[18:21]
	s_setprio 0
	s_nop 2
	v_pk_mul_f32 v[20:21], v[44:45], v[0:1] op_sel_hi:[1,0]
	v_pk_mul_f32 v[18:19], v[42:43], v[0:1] op_sel_hi:[1,0]
	s_nop 1
	v_mfma_f32_16x16x32_bf16 v[42:45], v[126:129], v[22:25], v[18:21]
	s_nop 2
	v_pk_mul_f32 v[20:21], v[48:49], v[0:1] op_sel_hi:[1,0]
	v_pk_mul_f32 v[18:19], v[46:47], v[0:1] op_sel_hi:[1,0]
	s_nop 1
	v_mfma_f32_16x16x32_bf16 v[46:49], v[130:133], v[22:25], v[18:21]
